# adds: weight-conversion gain loads issued as one batch with counted waits (4 sites)
# baseline (speedup 1.0000x reference)
; __device__ __forceinline__ void p0_item(const float* W, const float* gain, int K, int N, bf16_t* WT, int mode, LAS float* scr, int item, int lane) {
;     const int nblk = N / 64, kb = item / nblk, nb = item % nblk, k0 = 64 * kb, n0 = 64 * nb;
;     const int kr = lane >> 4, nc = (lane & 15) * 4;
;     f32x4 v[16];
; #pragma unroll
;     for (int i = 0; i < 16; ++i) v[i] = __builtin_nontemporal_load((const f32x4*)(W + (size_t)(k0 + 4 * i + kr) * N + n0 + nc));
;     if (gain) {
.LBB0_114:
	s_or_b64 exec, exec, s[8:9]
	v_lshrrev_b32_e32 v5, 6, v58
	v_cvt_f32_u32_e32 v6, v5
	v_sub_u32_e32 v9, 0, v5
	v_sub_u32_e32 v8, 0, v4
	v_max_i32_e32 v8, v4, v8
	v_rcp_iflag_f32_e32 v6, v6
	v_ashrrev_i32_e32 v7, 31, v4
	v_mul_f32_e32 v6, 0x4f7ffffe, v6
	v_cvt_u32_f32_e32 v6, v6
	v_mul_lo_u32 v9, v9, v6
	v_mul_hi_u32 v9, v6, v9
	v_add_u32_e32 v6, v6, v9
	v_mul_hi_u32 v6, v8, v6
	v_mul_lo_u32 v9, v6, v5
	v_sub_u32_e32 v8, v8, v9
	v_add_u32_e32 v10, 1, v6
	v_cmp_ge_u32_e32 vcc, v8, v5
	v_sub_u32_e32 v9, v8, v5
	s_nop 0
	v_cndmask_b32_e32 v6, v6, v10, vcc
	v_cndmask_b32_e32 v8, v8, v9, vcc
	v_add_u32_e32 v9, 1, v6
	v_cmp_ge_u32_e32 vcc, v8, v5
	s_nop 1
	v_cndmask_b32_e32 v6, v6, v9, vcc
	v_xor_b32_e32 v6, v6, v7
	v_sub_u32_e32 v6, v6, v7
	v_mul_lo_u32 v5, v6, v5
	v_sub_u32_e32 v73, v4, v5
	v_lshlrev_b32_e32 v72, 6, v6
	v_lshlrev_b32_e32 v74, 6, v73
	v_or_b32_e32 v78, v72, v81
	v_ashrrev_i32_e32 v75, 31, v74
	v_or_b32_e32 v59, 56, v78
	v_lshl_add_u64 v[2:3], v[74:75], 2, v[2:3]
	v_ashrrev_i32_e32 v79, 31, v78
	v_or_b32_e32 v4, 4, v78
	v_or_b32_e32 v10, 8, v78
	v_or_b32_e32 v12, 12, v78
	v_or_b32_e32 v18, 16, v78
	v_or_b32_e32 v20, 20, v78
	v_or_b32_e32 v26, 24, v78
	v_or_b32_e32 v28, 28, v78
	v_or_b32_e32 v34, 32, v78
	v_or_b32_e32 v36, 36, v78
	v_or_b32_e32 v42, 40, v78
	v_or_b32_e32 v44, 44, v78
	v_or_b32_e32 v50, 48, v78
	v_or_b32_e32 v52, 52, v78
	v_mad_u64_u32 v[62:63], s[8:9], v59, v58, 0
	v_or_b32_e32 v59, 60, v78
	v_lshl_add_u64 v[60:61], v[2:3], 0, v[0:1]
	v_mul_lo_u32 v64, v79, v58
	v_mad_u64_u32 v[2:3], s[8:9], v78, v58, 0
	v_mad_u64_u32 v[4:5], s[8:9], v4, v58, 0
	v_mad_u64_u32 v[10:11], s[8:9], v10, v58, 0
	v_mad_u64_u32 v[12:13], s[8:9], v12, v58, 0
	v_mad_u64_u32 v[18:19], s[8:9], v18, v58, 0
	v_mad_u64_u32 v[20:21], s[8:9], v20, v58, 0
	v_mad_u64_u32 v[26:27], s[8:9], v26, v58, 0
	v_mad_u64_u32 v[28:29], s[8:9], v28, v58, 0
	v_mad_u64_u32 v[34:35], s[8:9], v34, v58, 0
	v_mad_u64_u32 v[36:37], s[8:9], v36, v58, 0
	v_mad_u64_u32 v[42:43], s[8:9], v42, v58, 0
	v_mad_u64_u32 v[44:45], s[8:9], v44, v58, 0
	v_mad_u64_u32 v[50:51], s[8:9], v50, v58, 0
	v_mad_u64_u32 v[52:53], s[8:9], v52, v58, 0
	v_mad_u64_u32 v[58:59], s[8:9], v59, v58, 0
	v_add_u32_e32 v3, v3, v64
	v_add_u32_e32 v5, v5, v64
	v_add_u32_e32 v11, v11, v64
	v_add_u32_e32 v13, v13, v64
	v_add_u32_e32 v19, v19, v64
	v_add_u32_e32 v21, v21, v64
	v_add_u32_e32 v27, v27, v64
	v_add_u32_e32 v29, v29, v64
	v_add_u32_e32 v35, v35, v64
	v_add_u32_e32 v37, v37, v64
	v_add_u32_e32 v43, v43, v64
	v_add_u32_e32 v45, v45, v64
	v_add_u32_e32 v51, v51, v64
	v_add_u32_e32 v53, v53, v64
	v_add_u32_e32 v63, v63, v64
	v_add_u32_e32 v59, v59, v64
	v_lshl_add_u64 v[2:3], v[2:3], 2, v[60:61]
	v_lshl_add_u64 v[4:5], v[4:5], 2, v[60:61]
	v_lshl_add_u64 v[10:11], v[10:11], 2, v[60:61]
	v_lshl_add_u64 v[12:13], v[12:13], 2, v[60:61]
	v_lshl_add_u64 v[18:19], v[18:19], 2, v[60:61]
	v_lshl_add_u64 v[20:21], v[20:21], 2, v[60:61]
	v_lshl_add_u64 v[26:27], v[26:27], 2, v[60:61]
	v_lshl_add_u64 v[28:29], v[28:29], 2, v[60:61]
	v_lshl_add_u64 v[34:35], v[34:35], 2, v[60:61]
	v_lshl_add_u64 v[36:37], v[36:37], 2, v[60:61]
	v_lshl_add_u64 v[42:43], v[42:43], 2, v[60:61]
	v_lshl_add_u64 v[44:45], v[44:45], 2, v[60:61]
	v_lshl_add_u64 v[50:51], v[50:51], 2, v[60:61]
	v_lshl_add_u64 v[52:53], v[52:53], 2, v[60:61]
	v_lshl_add_u64 v[62:63], v[62:63], 2, v[60:61]
	v_lshl_add_u64 v[58:59], v[58:59], 2, v[60:61]
	global_load_dwordx4 v[6:9], v[2:3], off nt
	s_nop 0
	global_load_dwordx4 v[2:5], v[4:5], off nt
	s_nop 0
	global_load_dwordx4 v[14:17], v[10:11], off nt
	s_nop 0
	global_load_dwordx4 v[10:13], v[12:13], off nt
	s_nop 0
	global_load_dwordx4 v[22:25], v[18:19], off nt
	s_nop 0
	global_load_dwordx4 v[18:21], v[20:21], off nt
	s_nop 0
	global_load_dwordx4 v[30:33], v[26:27], off nt
	s_nop 0
	global_load_dwordx4 v[26:29], v[28:29], off nt
	s_nop 0
	global_load_dwordx4 v[38:41], v[34:35], off nt
	s_nop 0
	global_load_dwordx4 v[34:37], v[36:37], off nt
	s_nop 0
	global_load_dwordx4 v[46:49], v[42:43], off nt
	s_nop 0
	global_load_dwordx4 v[42:45], v[44:45], off nt
	s_nop 0
	global_load_dwordx4 v[54:57], v[50:51], off nt
	s_nop 0
	global_load_dwordx4 v[50:53], v[52:53], off nt
	s_nop 0
	global_load_dwordx4 v[62:65], v[62:63], off nt
	s_nop 0
	global_load_dwordx4 v[58:61], v[58:59], off nt
	v_cmp_ne_u64_e32 vcc, 0, v[76:77]
	s_and_saveexec_b64 s[8:9], vcc
	s_cbranch_execz .LBB0_105
; __device__ __forceinline__ void p0_item(const float* W, const float* gain, int K, int N, bf16_t* WT, int mode, LAS float* scr, int item, int lane) {
;     ...
;     if (gain) {
; #pragma unroll
;         for (int i = 0; i < 16; ++i) v[i] = v[i] * gain[k0 + 4 * i + kr];
;     }
	v_lshl_add_u64 v[76:77], v[78:79], 2, v[76:77]
	global_load_dword v94, v[76:77], off
	global_load_dword v96, v[76:77], off offset:16
	global_load_dword v98, v[76:77], off offset:32
	global_load_dword v100, v[76:77], off offset:48
	global_load_dword v102, v[76:77], off offset:64
	global_load_dword v104, v[76:77], off offset:80
	global_load_dword v106, v[76:77], off offset:96
	global_load_dword v108, v[76:77], off offset:112
	global_load_dword v110, v[76:77], off offset:128
	global_load_dword v112, v[76:77], off offset:144
	global_load_dword v114, v[76:77], off offset:160
	global_load_dword v116, v[76:77], off offset:176
	global_load_dword v118, v[76:77], off offset:192
	global_load_dword v120, v[76:77], off offset:208
	global_load_dword v122, v[76:77], off offset:224
	s_nop 0
	global_load_dword v76, v[76:77], off offset:240
	s_waitcnt vmcnt(15)
	v_pk_mul_f32 v[8:9], v[8:9], v[94:95] op_sel_hi:[1,0]
	v_pk_mul_f32 v[6:7], v[6:7], v[94:95] op_sel_hi:[1,0]
	s_waitcnt vmcnt(14)
	v_pk_mul_f32 v[4:5], v[4:5], v[96:97] op_sel_hi:[1,0]
	v_pk_mul_f32 v[2:3], v[2:3], v[96:97] op_sel_hi:[1,0]
	s_waitcnt vmcnt(13)
	v_pk_mul_f32 v[16:17], v[16:17], v[98:99] op_sel_hi:[1,0]
	v_pk_mul_f32 v[14:15], v[14:15], v[98:99] op_sel_hi:[1,0]
	s_waitcnt vmcnt(12)
	v_pk_mul_f32 v[12:13], v[12:13], v[100:101] op_sel_hi:[1,0]
	v_pk_mul_f32 v[10:11], v[10:11], v[100:101] op_sel_hi:[1,0]
	s_waitcnt vmcnt(11)
	v_pk_mul_f32 v[24:25], v[24:25], v[102:103] op_sel_hi:[1,0]
	v_pk_mul_f32 v[22:23], v[22:23], v[102:103] op_sel_hi:[1,0]
	s_waitcnt vmcnt(10)
	v_pk_mul_f32 v[20:21], v[20:21], v[104:105] op_sel_hi:[1,0]
	v_pk_mul_f32 v[18:19], v[18:19], v[104:105] op_sel_hi:[1,0]
	s_waitcnt vmcnt(9)
	v_pk_mul_f32 v[32:33], v[32:33], v[106:107] op_sel_hi:[1,0]
	v_pk_mul_f32 v[30:31], v[30:31], v[106:107] op_sel_hi:[1,0]
	s_waitcnt vmcnt(8)
	v_pk_mul_f32 v[28:29], v[28:29], v[108:109] op_sel_hi:[1,0]
	v_pk_mul_f32 v[26:27], v[26:27], v[108:109] op_sel_hi:[1,0]
	s_waitcnt vmcnt(7)
	v_pk_mul_f32 v[40:41], v[40:41], v[110:111] op_sel_hi:[1,0]
	v_pk_mul_f32 v[38:39], v[38:39], v[110:111] op_sel_hi:[1,0]
	s_waitcnt vmcnt(6)
	v_pk_mul_f32 v[36:37], v[36:37], v[112:113] op_sel_hi:[1,0]
	v_pk_mul_f32 v[34:35], v[34:35], v[112:113] op_sel_hi:[1,0]
	s_waitcnt vmcnt(5)
	v_pk_mul_f32 v[48:49], v[48:49], v[114:115] op_sel_hi:[1,0]
	v_pk_mul_f32 v[46:47], v[46:47], v[114:115] op_sel_hi:[1,0]
	s_waitcnt vmcnt(4)
	v_pk_mul_f32 v[44:45], v[44:45], v[116:117] op_sel_hi:[1,0]
	v_pk_mul_f32 v[42:43], v[42:43], v[116:117] op_sel_hi:[1,0]
	s_waitcnt vmcnt(3)
	v_pk_mul_f32 v[56:57], v[56:57], v[118:119] op_sel_hi:[1,0]
	v_pk_mul_f32 v[54:55], v[54:55], v[118:119] op_sel_hi:[1,0]
	s_waitcnt vmcnt(2)
	v_pk_mul_f32 v[52:53], v[52:53], v[120:121] op_sel_hi:[1,0]
	v_pk_mul_f32 v[50:51], v[50:51], v[120:121] op_sel_hi:[1,0]
	s_waitcnt vmcnt(1)
	v_pk_mul_f32 v[64:65], v[64:65], v[122:123] op_sel_hi:[1,0]
	v_pk_mul_f32 v[62:63], v[62:63], v[122:123] op_sel_hi:[1,0]
	s_waitcnt vmcnt(0)
	v_pk_mul_f32 v[60:61], v[60:61], v[76:77] op_sel_hi:[1,0]
	v_pk_mul_f32 v[58:59], v[58:59], v[76:77] op_sel_hi:[1,0]
	s_branch .LBB0_105

; __device__ __forceinline__ void p0_item(const float* W, const float* gain, int K, int N, bf16_t* WT, int mode, LAS float* scr, int item, int lane) {
;     const int nblk = N / 64, kb = item / nblk, nb = item % nblk, k0 = 64 * kb, n0 = 64 * nb;
;     const int kr = lane >> 4, nc = (lane & 15) * 4;
;     f32x4 v[16];
; #pragma unroll
;     for (int i = 0; i < 16; ++i) v[i] = __builtin_nontemporal_load((const f32x4*)(W + (size_t)(k0 + 4 * i + kr) * N + n0 + nc));
;     if (gain) {
.LBB0_353:
	s_or_b64 exec, exec, s[0:1]
	v_lshrrev_b32_e32 v5, 6, v58
	v_cvt_f32_u32_e32 v6, v5
	v_sub_u32_e32 v9, 0, v5
	v_sub_u32_e32 v8, 0, v4
	v_max_i32_e32 v8, v4, v8
	v_rcp_iflag_f32_e32 v6, v6
	v_ashrrev_i32_e32 v7, 31, v4
	v_mul_f32_e32 v6, 0x4f7ffffe, v6
	v_cvt_u32_f32_e32 v6, v6
	v_mul_lo_u32 v9, v9, v6
	v_mul_hi_u32 v9, v6, v9
	v_add_u32_e32 v6, v6, v9
	v_mul_hi_u32 v6, v8, v6
	v_mul_lo_u32 v9, v6, v5
	v_sub_u32_e32 v8, v8, v9
	v_add_u32_e32 v10, 1, v6
	v_cmp_ge_u32_e64 s[0:1], v8, v5
	v_sub_u32_e32 v9, v8, v5
	s_nop 0
	v_cndmask_b32_e64 v6, v6, v10, s[0:1]
	v_cndmask_b32_e64 v8, v8, v9, s[0:1]
	v_add_u32_e32 v9, 1, v6
	v_cmp_ge_u32_e64 s[0:1], v8, v5
	s_nop 1
	v_cndmask_b32_e64 v6, v6, v9, s[0:1]
	v_xor_b32_e32 v6, v6, v7
	v_sub_u32_e32 v6, v6, v7
	v_mul_lo_u32 v5, v6, v5
	v_sub_u32_e32 v75, v4, v5
	v_lshlrev_b32_e32 v74, 6, v6
	v_lshlrev_b32_e32 v76, 6, v75
	v_or_b32_e32 v78, v74, v81
	v_ashrrev_i32_e32 v77, 31, v76
	v_or_b32_e32 v59, 56, v78
	v_lshl_add_u64 v[2:3], v[76:77], 2, v[2:3]
	v_ashrrev_i32_e32 v79, 31, v78
	v_or_b32_e32 v4, 4, v78
	v_or_b32_e32 v10, 8, v78
	v_or_b32_e32 v12, 12, v78
	v_or_b32_e32 v18, 16, v78
	v_or_b32_e32 v20, 20, v78
	v_or_b32_e32 v26, 24, v78
	v_or_b32_e32 v28, 28, v78
	v_or_b32_e32 v34, 32, v78
	v_or_b32_e32 v36, 36, v78
	v_or_b32_e32 v42, 40, v78
	v_or_b32_e32 v44, 44, v78
	v_or_b32_e32 v50, 48, v78
	v_or_b32_e32 v52, 52, v78
	v_mad_u64_u32 v[62:63], s[0:1], v59, v58, 0
	v_or_b32_e32 v59, 60, v78
	v_lshl_add_u64 v[60:61], v[2:3], 0, v[0:1]
	v_mul_lo_u32 v64, v79, v58
	v_mad_u64_u32 v[2:3], s[0:1], v78, v58, 0
	v_mad_u64_u32 v[4:5], s[0:1], v4, v58, 0
	v_mad_u64_u32 v[10:11], s[0:1], v10, v58, 0
	v_mad_u64_u32 v[12:13], s[0:1], v12, v58, 0
	v_mad_u64_u32 v[18:19], s[0:1], v18, v58, 0
	v_mad_u64_u32 v[20:21], s[0:1], v20, v58, 0
	v_mad_u64_u32 v[26:27], s[0:1], v26, v58, 0
	v_mad_u64_u32 v[28:29], s[0:1], v28, v58, 0
	v_mad_u64_u32 v[34:35], s[0:1], v34, v58, 0
	v_mad_u64_u32 v[36:37], s[0:1], v36, v58, 0
	v_mad_u64_u32 v[42:43], s[0:1], v42, v58, 0
	v_mad_u64_u32 v[44:45], s[0:1], v44, v58, 0
	v_mad_u64_u32 v[50:51], s[0:1], v50, v58, 0
	v_mad_u64_u32 v[52:53], s[0:1], v52, v58, 0
	v_mad_u64_u32 v[58:59], s[0:1], v59, v58, 0
	v_add_u32_e32 v3, v3, v64
	v_add_u32_e32 v5, v5, v64
	v_add_u32_e32 v11, v11, v64
	v_add_u32_e32 v13, v13, v64
	v_add_u32_e32 v19, v19, v64
	v_add_u32_e32 v21, v21, v64
	v_add_u32_e32 v27, v27, v64
	v_add_u32_e32 v29, v29, v64
	v_add_u32_e32 v35, v35, v64
	v_add_u32_e32 v37, v37, v64
	v_add_u32_e32 v43, v43, v64
	v_add_u32_e32 v45, v45, v64
	v_add_u32_e32 v51, v51, v64
	v_add_u32_e32 v53, v53, v64
	v_add_u32_e32 v63, v63, v64
	v_add_u32_e32 v59, v59, v64
	v_lshl_add_u64 v[2:3], v[2:3], 2, v[60:61]
	v_lshl_add_u64 v[4:5], v[4:5], 2, v[60:61]
	v_lshl_add_u64 v[10:11], v[10:11], 2, v[60:61]
	v_lshl_add_u64 v[12:13], v[12:13], 2, v[60:61]
	v_lshl_add_u64 v[18:19], v[18:19], 2, v[60:61]
	v_lshl_add_u64 v[20:21], v[20:21], 2, v[60:61]
	v_lshl_add_u64 v[26:27], v[26:27], 2, v[60:61]
	v_lshl_add_u64 v[28:29], v[28:29], 2, v[60:61]
	v_lshl_add_u64 v[34:35], v[34:35], 2, v[60:61]
	v_lshl_add_u64 v[36:37], v[36:37], 2, v[60:61]
	v_lshl_add_u64 v[42:43], v[42:43], 2, v[60:61]
	v_lshl_add_u64 v[44:45], v[44:45], 2, v[60:61]
	v_lshl_add_u64 v[50:51], v[50:51], 2, v[60:61]
	v_lshl_add_u64 v[52:53], v[52:53], 2, v[60:61]
	v_lshl_add_u64 v[62:63], v[62:63], 2, v[60:61]
	v_lshl_add_u64 v[58:59], v[58:59], 2, v[60:61]
	global_load_dwordx4 v[6:9], v[2:3], off nt
	s_nop 0
	global_load_dwordx4 v[2:5], v[4:5], off nt
	s_nop 0
	global_load_dwordx4 v[14:17], v[10:11], off nt
	s_nop 0
	global_load_dwordx4 v[10:13], v[12:13], off nt
	s_nop 0
	global_load_dwordx4 v[22:25], v[18:19], off nt
	s_nop 0
	global_load_dwordx4 v[18:21], v[20:21], off nt
	s_nop 0
	global_load_dwordx4 v[30:33], v[26:27], off nt
	s_nop 0
	global_load_dwordx4 v[26:29], v[28:29], off nt
	s_nop 0
	global_load_dwordx4 v[38:41], v[34:35], off nt
	s_nop 0
	global_load_dwordx4 v[34:37], v[36:37], off nt
	s_nop 0
	global_load_dwordx4 v[46:49], v[42:43], off nt
	s_nop 0
	global_load_dwordx4 v[42:45], v[44:45], off nt
	s_nop 0
	global_load_dwordx4 v[54:57], v[50:51], off nt
	s_nop 0
	global_load_dwordx4 v[50:53], v[52:53], off nt
	s_nop 0
	global_load_dwordx4 v[62:65], v[62:63], off nt
	s_nop 0
	global_load_dwordx4 v[58:61], v[58:59], off nt
	v_cmp_ne_u64_e64 s[0:1], 0, v[72:73]
	s_and_saveexec_b64 s[10:11], s[0:1]
	s_cbranch_execz .LBB0_316
; __device__ __forceinline__ void p0_item(const float* W, const float* gain, int K, int N, bf16_t* WT, int mode, LAS float* scr, int item, int lane) {
;     ...
;     if (gain) {
; #pragma unroll
;         for (int i = 0; i < 16; ++i) v[i] = v[i] * gain[k0 + 4 * i + kr];
;     }
	v_lshl_add_u64 v[72:73], v[78:79], 2, v[72:73]
	global_load_dword v94, v[72:73], off
	global_load_dword v96, v[72:73], off offset:16
	global_load_dword v98, v[72:73], off offset:32
	global_load_dword v100, v[72:73], off offset:48
	global_load_dword v102, v[72:73], off offset:64
	global_load_dword v104, v[72:73], off offset:80
	global_load_dword v106, v[72:73], off offset:96
	global_load_dword v108, v[72:73], off offset:112
	global_load_dword v110, v[72:73], off offset:128
	global_load_dword v112, v[72:73], off offset:144
	global_load_dword v114, v[72:73], off offset:160
	global_load_dword v116, v[72:73], off offset:176
	global_load_dword v118, v[72:73], off offset:192
	global_load_dword v120, v[72:73], off offset:208
	global_load_dword v122, v[72:73], off offset:224
	s_nop 0
	global_load_dword v72, v[72:73], off offset:240
	s_waitcnt vmcnt(15)
	v_pk_mul_f32 v[8:9], v[8:9], v[94:95] op_sel_hi:[1,0]
	v_pk_mul_f32 v[6:7], v[6:7], v[94:95] op_sel_hi:[1,0]
	s_waitcnt vmcnt(14)
	v_pk_mul_f32 v[4:5], v[4:5], v[96:97] op_sel_hi:[1,0]
	v_pk_mul_f32 v[2:3], v[2:3], v[96:97] op_sel_hi:[1,0]
	s_waitcnt vmcnt(13)
	v_pk_mul_f32 v[16:17], v[16:17], v[98:99] op_sel_hi:[1,0]
	v_pk_mul_f32 v[14:15], v[14:15], v[98:99] op_sel_hi:[1,0]
	s_waitcnt vmcnt(12)
	v_pk_mul_f32 v[12:13], v[12:13], v[100:101] op_sel_hi:[1,0]
	v_pk_mul_f32 v[10:11], v[10:11], v[100:101] op_sel_hi:[1,0]
	s_waitcnt vmcnt(11)
	v_pk_mul_f32 v[24:25], v[24:25], v[102:103] op_sel_hi:[1,0]
	v_pk_mul_f32 v[22:23], v[22:23], v[102:103] op_sel_hi:[1,0]
	s_waitcnt vmcnt(10)
	v_pk_mul_f32 v[20:21], v[20:21], v[104:105] op_sel_hi:[1,0]
	v_pk_mul_f32 v[18:19], v[18:19], v[104:105] op_sel_hi:[1,0]
	s_waitcnt vmcnt(9)
	v_pk_mul_f32 v[32:33], v[32:33], v[106:107] op_sel_hi:[1,0]
	v_pk_mul_f32 v[30:31], v[30:31], v[106:107] op_sel_hi:[1,0]
	s_waitcnt vmcnt(8)
	v_pk_mul_f32 v[28:29], v[28:29], v[108:109] op_sel_hi:[1,0]
	v_pk_mul_f32 v[26:27], v[26:27], v[108:109] op_sel_hi:[1,0]
	s_waitcnt vmcnt(7)
	v_pk_mul_f32 v[40:41], v[40:41], v[110:111] op_sel_hi:[1,0]
	v_pk_mul_f32 v[38:39], v[38:39], v[110:111] op_sel_hi:[1,0]
	s_waitcnt vmcnt(6)
	v_pk_mul_f32 v[36:37], v[36:37], v[112:113] op_sel_hi:[1,0]
	v_pk_mul_f32 v[34:35], v[34:35], v[112:113] op_sel_hi:[1,0]
	s_waitcnt vmcnt(5)
	v_pk_mul_f32 v[48:49], v[48:49], v[114:115] op_sel_hi:[1,0]
	v_pk_mul_f32 v[46:47], v[46:47], v[114:115] op_sel_hi:[1,0]
	s_waitcnt vmcnt(4)
	v_pk_mul_f32 v[44:45], v[44:45], v[116:117] op_sel_hi:[1,0]
	v_pk_mul_f32 v[42:43], v[42:43], v[116:117] op_sel_hi:[1,0]
	s_waitcnt vmcnt(3)
	v_pk_mul_f32 v[56:57], v[56:57], v[118:119] op_sel_hi:[1,0]
	v_pk_mul_f32 v[54:55], v[54:55], v[118:119] op_sel_hi:[1,0]
	s_waitcnt vmcnt(2)
	v_pk_mul_f32 v[52:53], v[52:53], v[120:121] op_sel_hi:[1,0]
	v_pk_mul_f32 v[50:51], v[50:51], v[120:121] op_sel_hi:[1,0]
	s_waitcnt vmcnt(1)
	v_pk_mul_f32 v[64:65], v[64:65], v[122:123] op_sel_hi:[1,0]
	v_pk_mul_f32 v[62:63], v[62:63], v[122:123] op_sel_hi:[1,0]
	s_waitcnt vmcnt(0)
	v_pk_mul_f32 v[60:61], v[60:61], v[72:73] op_sel_hi:[1,0]
	v_pk_mul_f32 v[58:59], v[58:59], v[72:73] op_sel_hi:[1,0]
	s_branch .LBB0_316
